# v48 + attention setup: serial 64-step prefix maximum of the key-norm tile maxima (one wave, every unit) replaced by a 64-lane DPP scan (exact same max)
# speedup vs baseline: 1.0095x; 1.0091x over previous
; #define LAS __attribute__((address_space(3)))
; #define ATT_STORE(buf) do { ATT_STORE1((buf) * 2, kreg[0], vreg[0]); ATT_STORE1((buf) * 2 + 1, kreg[1], vreg[1]); } while (0)
; template <bool MOBA>
; __device__ __forceinline__ void attn_unit(unsigned char* lds, LAS unsigned char* lds3, const Params& p, int b, int h, int qb) {
;     ...
;         for (int bk = 0; bk < 32; ++bk) bmax = fmaxf(bmax, relb[bk * 8 + h] * LOG2E);
;         __syncthreads();
;         if (tid < 256) {
;             const bf16_t* qp = Qg + (rowbase + qb * 256 + tid) * DM + hcol; float qv[64];
; #pragma unroll
;             for (int c = 0; c < 8; ++c) { const u32x4 v = *(const u32x4*)(qp + c * 8);
; #pragma unroll
;                 for (int j = 0; j < 4; ++j) { qv[c * 8 + 2 * j] = bf_lo(v[j]); qv[c * 8 + 2 * j + 1] = bf_hi(v[j]); } }
;             float v1 = -INFINITY, v2 = -INFINITY, v3 = -INFINITY; int i1 = -1, i2 = -1, i3 = -1;
;             for (int j = 0; j < qb; ++j) { float d = 0.f;
; #pragma unroll
;                 for (int c = 0; c < 16; ++c) { const f32x4 kv = *(const LAS f32x4*)(kms + j * 64 + c * 4); d += qv[4 * c] * kv[0] + qv[4 * c + 1] * kv[1] + qv[4 * c + 2] * kv[2] + qv[4 * c + 3] * kv[3]; }
;                 if (d > v1) { v3 = v2; i3 = i2; v2 = v1; i2 = i1; v1 = d; i1 = j; } else if (d > v2) { v3 = v2; i3 = i2; v2 = d; i2 = j; } else if (d > v3) { v3 = d; i3 = j; } }
;             unsigned mask = 0u; if (i1 >= 0) mask |= 1u << i1; if (i2 >= 0) mask |= 1u << i2; if (i3 >= 0) mask |= 1u << i3;
;             sel[tid] = mask | (1u << qb);
;         }
;     }
;     const int vswz = (skey ^ (sch << 3));
;     ...
;     ATT_STORE(0);
;     __syncthreads();
;     if (tid < 64) { float pm = 0.f; for (int t = 0; t <= tid; ++t) pm = fmaxf(pm, kpms[64 + t]); kpms[tid] = sqrtf(pm) * 1.002f; }
.LBB0_397:
	s_or_b64 exec, exec, s[10:11]
	s_waitcnt vmcnt(31)
	v_mul_f32_e32 v42, 0x3fb8aa3b, v130
	s_waitcnt vmcnt(30)
	v_mul_f32_e32 v43, 0x3fb8aa3b, v131
	v_max3_f32 v42, v42, s93, v43
	s_waitcnt vmcnt(29)
	v_mul_f32_e32 v43, 0x3fb8aa3b, v128
	s_waitcnt vmcnt(28)
	v_mul_f32_e32 v44, 0x3fb8aa3b, v129
	v_max3_f32 v42, v42, v43, v44
	s_waitcnt vmcnt(27)
	v_mul_f32_e32 v43, 0x3fb8aa3b, v126
	s_waitcnt vmcnt(26)
	v_mul_f32_e32 v44, 0x3fb8aa3b, v127
	v_max3_f32 v42, v42, v43, v44
	s_waitcnt vmcnt(25)
	v_mul_f32_e32 v43, 0x3fb8aa3b, v124
	s_waitcnt vmcnt(24)
	v_mul_f32_e32 v44, 0x3fb8aa3b, v125
	v_max3_f32 v42, v42, v43, v44
	s_waitcnt vmcnt(23)
	v_mul_f32_e32 v43, 0x3fb8aa3b, v122
	s_waitcnt vmcnt(22)
	v_mul_f32_e32 v44, 0x3fb8aa3b, v123
	v_max3_f32 v42, v42, v43, v44
	s_waitcnt vmcnt(21)
	v_mul_f32_e32 v43, 0x3fb8aa3b, v120
	s_waitcnt vmcnt(20)
	v_mul_f32_e32 v44, 0x3fb8aa3b, v121
	v_max3_f32 v42, v42, v43, v44
	s_waitcnt vmcnt(19)
	v_mul_f32_e32 v43, 0x3fb8aa3b, v114
	s_waitcnt vmcnt(18)
	v_mul_f32_e32 v44, 0x3fb8aa3b, v115
	v_max3_f32 v42, v42, v43, v44
	s_waitcnt vmcnt(17)
	v_mul_f32_e32 v43, 0x3fb8aa3b, v112
	s_waitcnt vmcnt(16)
	v_mul_f32_e32 v44, 0x3fb8aa3b, v113
	v_max3_f32 v42, v42, v43, v44
	s_waitcnt vmcnt(15)
	v_mul_f32_e32 v43, 0x3fb8aa3b, v110
	s_waitcnt vmcnt(14)
	v_mul_f32_e32 v44, 0x3fb8aa3b, v111
	v_max3_f32 v42, v42, v43, v44
	s_waitcnt vmcnt(13)
	v_mul_f32_e32 v43, 0x3fb8aa3b, v102
	s_waitcnt vmcnt(12)
	v_mul_f32_e32 v44, 0x3fb8aa3b, v103
	v_max3_f32 v42, v42, v43, v44
	s_waitcnt vmcnt(11)
	v_mul_f32_e32 v43, 0x3fb8aa3b, v100
	s_waitcnt vmcnt(10)
	v_mul_f32_e32 v44, 0x3fb8aa3b, v101
	v_max3_f32 v42, v42, v43, v44
	s_waitcnt vmcnt(9)
	v_mul_f32_e32 v43, 0x3fb8aa3b, v96
	s_waitcnt vmcnt(8)
	v_mul_f32_e32 v44, 0x3fb8aa3b, v97
	v_max3_f32 v42, v42, v43, v44
	s_waitcnt vmcnt(6)
	v_mul_f32_e32 v43, 0x3fb8aa3b, v98
	s_waitcnt vmcnt(5)
	v_mul_f32_e32 v44, 0x3fb8aa3b, v99
	v_max3_f32 v42, v42, v43, v44
	s_waitcnt vmcnt(4)
	v_mul_f32_e32 v43, 0x3fb8aa3b, v94
	s_waitcnt vmcnt(3)
	v_mul_f32_e32 v44, 0x3fb8aa3b, v95
	v_max3_f32 v42, v42, v43, v44
	s_waitcnt vmcnt(2)
	v_mul_f32_e32 v43, 0x3fb8aa3b, v92
	s_waitcnt vmcnt(1)
	v_mul_f32_e32 v44, 0x3fb8aa3b, v93
	v_max3_f32 v42, v42, v43, v44
	s_waitcnt vmcnt(0)
	v_mul_f32_e32 v43, 0x3fb8aa3b, v91
	v_mul_f32_e32 v133, 0x3fb8aa3b, v41
	s_movk_i32 s3, 0x90
	v_max3_f32 v42, v42, v43, v133
	v_mul_lo_u32 v43, v106, s3
	v_xor_b32_e32 v41, v90, v106
	v_add3_u32 v134, 0, v43, v40
	ds_write_b128 v134, v[32:35]
	v_mul_u32_u24_e32 v32, 0x90, v90
	v_lshlrev_b32_e32 v33, 1, v41
	v_add3_u32 v135, 0, v32, v33
	ds_write_b16 v135, v20 offset:36864
	ds_write_b16_d16_hi v135, v20 offset:37008
	ds_write_b16 v135, v21 offset:37152
	ds_write_b16_d16_hi v135, v21 offset:37296
	ds_write_b16 v135, v22 offset:37440
	ds_write_b16_d16_hi v135, v22 offset:37584
	ds_write_b16 v135, v23 offset:37728
	ds_write_b16_d16_hi v135, v23 offset:37872
	ds_write_b128 v134, v[28:31] offset:9216
	ds_write_b16 v135, v24 offset:46080
	ds_write_b16_d16_hi v135, v24 offset:46224
	ds_write_b16 v135, v25 offset:46368
	ds_write_b16_d16_hi v135, v25 offset:46512
	ds_write_b16 v135, v26 offset:46656
	ds_write_b16_d16_hi v135, v26 offset:46800
	ds_write_b16 v135, v27 offset:46944
	ds_write_b16_d16_hi v135, v27 offset:47088
	s_waitcnt lgkmcnt(0)
	s_barrier
	s_and_saveexec_b64 s[6:7], s[8:9]
	s_cbranch_execz .LBB0_409
	v_cmp_lt_i32_e32 vcc, -1, v104
	v_mov_b32_e32 v20, 0
	s_and_saveexec_b64 s[10:11], vcc
	s_cbranch_execz .LBB0_408
	v_lshl_add_u32 v21, v104, 2, 0
	v_add_u32_e32 v21, 0x16900, v21
	ds_read_b32 v22, v21
	s_mov_b64 s[8:9], exec
	s_waitcnt lgkmcnt(0)
	v_max_f32_e32 v22, v22, v22
	s_nop 1
	v_max_f32_dpp v22, v22, v22 row_shr:1 row_mask:0xf bank_mask:0xf bound_ctrl:1
	s_nop 1
	v_max_f32_dpp v22, v22, v22 row_shr:2 row_mask:0xf bank_mask:0xf bound_ctrl:1
	s_nop 1
	v_max_f32_dpp v22, v22, v22 row_shr:4 row_mask:0xf bank_mask:0xf bound_ctrl:1
	s_nop 1
	v_max_f32_dpp v22, v22, v22 row_shr:8 row_mask:0xf bank_mask:0xf bound_ctrl:1
	s_nop 1
	v_max_f32_dpp v22, v22, v22 row_bcast:15 row_mask:0xa bank_mask:0xf
	s_nop 1
	v_max_f32_dpp v22, v22, v22 row_bcast:31 row_mask:0xc bank_mask:0xf
	s_nop 1

; #define LAS __attribute__((address_space(3)))
; #define ATT_STORE(buf) do { ATT_STORE1((buf) * 2, kreg[0], vreg[0]); ATT_STORE1((buf) * 2 + 1, kreg[1], vreg[1]); } while (0)
; template <bool MOBA>
; __device__ __forceinline__ void attn_unit(unsigned char* lds, LAS unsigned char* lds3, const Params& p, int b, int h, int qb) {
;     ...
;         if (tid < 16) dflag[tid] = 0u;
;     } else {
;         const float* km = (const float*)(p.ws + WS_KMEAN) + (((size_t)b * 8 + h) * 16) * 64; const float* relb = p.in[I_RELB];
;         for (int i = tid; i < 16 * 64; i += NTHREADS) kms[i] = km[i];
;         if (tid < 128) { int bk = tid; if (tid >= 16) { bk = 16 + (int)(logf((float)tid / 16.0f) / 2.0794415416798357f * 16.0f); bk = bk > 31 ? 31 : bk; } tbl[tid] = relb[bk * 8 + h] * LOG2E; }
;         c31 = relb[31 * 8 + h] * LOG2E;
;         for (int bk = 0; bk < 32; ++bk) bmax = fmaxf(bmax, relb[bk * 8 + h] * LOG2E);
;         __syncthreads();
;         if (tid < 256) {
;             const bf16_t* qp = Qg + (rowbase + qb * 256 + tid) * DM + hcol; float qv[64];
; #pragma unroll
;             for (int c = 0; c < 8; ++c) { const u32x4 v = *(const u32x4*)(qp + c * 8);
; #pragma unroll
;                 for (int j = 0; j < 4; ++j) { qv[c * 8 + 2 * j] = bf_lo(v[j]); qv[c * 8 + 2 * j + 1] = bf_hi(v[j]); } }
;             float v1 = -INFINITY, v2 = -INFINITY, v3 = -INFINITY; int i1 = -1, i2 = -1, i3 = -1;
;             for (int j = 0; j < qb; ++j) { float d = 0.f;
; #pragma unroll
;                 for (int c = 0; c < 16; ++c) { const f32x4 kv = *(const LAS f32x4*)(kms + j * 64 + c * 4); d += qv[4 * c] * kv[0] + qv[4 * c + 1] * kv[1] + qv[4 * c + 2] * kv[2] + qv[4 * c + 3] * kv[3]; }
;                 if (d > v1) { v3 = v2; i3 = i2; v2 = v1; i2 = i1; v1 = d; i1 = j; } else if (d > v2) { v3 = v2; i3 = i2; v2 = d; i2 = j; } else if (d > v3) { v3 = d; i3 = j; } }
;             unsigned mask = 0u; if (i1 >= 0) mask |= 1u << i1; if (i2 >= 0) mask |= 1u << i2; if (i3 >= 0) mask |= 1u << i3;
;             sel[tid] = mask | (1u << qb);
;         }
;     }
;     const int vswz = (skey ^ (sch << 3));
;     ...
;     ATT_STORE(0);
;     __syncthreads();
;     if (tid < 64) { float pm = 0.f; for (int t = 0; t <= tid; ++t) pm = fmaxf(pm, kpms[64 + t]); kpms[tid] = sqrtf(pm) * 1.002f; }
.LBB0_516:
	s_or_b64 exec, exec, s[10:11]
	v_cmp_gt_i32_e64 s[8:9], 16, v42
	v_lshl_add_u32 v38, v42, 2, 0
	s_and_saveexec_b64 s[10:11], s[8:9]
	v_add_u32_e32 v39, 0x16a00, v38
	ds_write_b32 v39, v0
	s_or_b64 exec, exec, s[10:11]
	s_movk_i32 s3, 0x90
	v_xor_b32_e32 v39, v46, v44
	v_mul_lo_u32 v40, v44, s3
	v_add3_u32 v115, 0, v40, v36
	v_mul_u32_u24_e32 v36, 0x90, v46
	v_lshlrev_b32_e32 v39, 1, v39
	v_add3_u32 v116, 0, v36, v39
	s_waitcnt vmcnt(7)
	ds_write_b128 v115, v[2:5]
	s_waitcnt vmcnt(6)
	ds_write_b16 v116, v30 offset:36864
	ds_write_b16_d16_hi v116, v30 offset:37008
	ds_write_b16 v116, v31 offset:37152
	ds_write_b16_d16_hi v116, v31 offset:37296
	ds_write_b16 v116, v32 offset:37440
	ds_write_b16_d16_hi v116, v32 offset:37584
	ds_write_b16 v116, v33 offset:37728
	ds_write_b16_d16_hi v116, v33 offset:37872
	s_waitcnt vmcnt(5)
	ds_write_b128 v115, v[14:17] offset:9216
	s_waitcnt vmcnt(4)
	ds_write_b16 v116, v26 offset:46080
	ds_write_b16_d16_hi v116, v26 offset:46224
	ds_write_b16 v116, v27 offset:46368
	ds_write_b16_d16_hi v116, v27 offset:46512
	ds_write_b16 v116, v28 offset:46656
	ds_write_b16_d16_hi v116, v28 offset:46800
	ds_write_b16 v116, v29 offset:46944
	ds_write_b16_d16_hi v116, v29 offset:47088
	s_waitcnt lgkmcnt(0)
	s_barrier
	s_and_saveexec_b64 s[10:11], vcc
	s_cbranch_execz .LBB0_530
	v_cmp_lt_i32_e32 vcc, -1, v42
	v_mov_b32_e32 v36, 0
	s_and_saveexec_b64 s[12:13], vcc
	s_cbranch_execz .LBB0_529
	v_add_u32_e32 v39, 0x16900, v38
	ds_read_b32 v40, v39
	s_mov_b64 s[8:9], exec
	s_waitcnt lgkmcnt(0)
	v_max_f32_e32 v40, v40, v40
	s_nop 1
	v_max_f32_dpp v40, v40, v40 row_shr:1 row_mask:0xf bank_mask:0xf bound_ctrl:1
	s_nop 1
	v_max_f32_dpp v40, v40, v40 row_shr:2 row_mask:0xf bank_mask:0xf bound_ctrl:1
	s_nop 1
	v_max_f32_dpp v40, v40, v40 row_shr:4 row_mask:0xf bank_mask:0xf bound_ctrl:1
	s_nop 1
	v_max_f32_dpp v40, v40, v40 row_shr:8 row_mask:0xf bank_mask:0xf bound_ctrl:1
	s_nop 1
	v_max_f32_dpp v40, v40, v40 row_bcast:15 row_mask:0xa bank_mask:0xf
	s_nop 1
	v_max_f32_dpp v40, v40, v40 row_bcast:31 row_mask:0xc bank_mask:0xf
	s_nop 1
